# two items per wave (waves 1..7) converted inside the grid barrier after in-proj(l)
# speedup vs baseline: 1.0407x; 1.0083x over previous
.LBB0_244:
	s_or_b64 exec, exec, s[2:3]
	v_readlane_b32 s6, v255, 59
	s_cmp_lt_u32 s78, 3
	s_cbranch_scc0 .Lgb_skip
	s_and_b32 s7, s6, 7
	s_cmp_eq_u32 s7, 0
	s_cbranch_scc1 .Lgb_skip
	s_lshr_b32 s9, s6, 3
	s_mul_i32 s9, s9, 7
	s_add_u32 s9, s9, s7
	s_sub_u32 s6, s9, 1
	v_readlane_b32 s82, v255, 57
	v_readlane_b32 s83, v255, 58
	v_readlane_b32 s84, v255, 53
	v_readlane_b32 s85, v255, 54
	v_readlane_b32 s92, v255, 60
	v_readlane_b32 s93, v255, 61
	v_readlane_b32 s40, v255, 6
	v_readlane_b32 s41, v255, 7
	v_readlane_b32 s42, v255, 8
	v_readlane_b32 s43, v255, 9
	v_and_b32_e32 v12, 63, v243
	v_lshrrev_b32_e32 v6, 3, v12
	v_and_b32_e32 v7, 7, v12
	v_lshlrev_b32_e32 v8, 4, v7
	v_lshl_or_b32 v2, v6, 18, v8
	v_lshl_or_b32 v3, v6, 16, v8
	v_lshlrev_b32_e32 v11, 5, v6
	v_lshlrev_b32_e32 v9, 4, v6
	v_lshl_or_b32 v5, v7, 14, v9
	s_sub_u32 s47, 1, s78
	s_mul_i32 s47, s47, 0x2800
	s_add_u32 s7, s47, s6
	s_add_u32 s47, s6, 0x2000
	s_cmp_eq_u32 s78, 2
	s_cselect_b32 s7, s47, s7
	s_mul_hi_u32 s9, s7, 0x66666667
	s_lshr_b32 s9, s9, 12
	s_mul_i32 s10, s9, 0x2800
	s_sub_u32 s10, s7, s10
	s_sub_u32 s9, 3, s9
	s_cmp_lt_u32 s10, 0x2000
	s_cselect_b64 s[12:13], -1, 0
	s_cselect_b32 s11, 0, 0x2000
	s_cselect_b32 s14, 7, 5
	s_cselect_b32 s15, 15, 13
	s_cselect_b32 s48, 26, 24
	s_cselect_b32 s17, 25, 23
	s_cselect_b32 s20, s84, s92
	s_cselect_b32 s21, s85, s93
	s_cselect_b32 s22, s40, s42
	s_cselect_b32 s23, s41, s43
	s_sub_u32 s10, s10, s11
	s_lshr_b32 s24, s10, 3
	s_lshr_b32 s25, s24, s14
	s_lshl_b32 s26, s25, s14
	s_sub_u32 s24, s24, s26
	s_and_b32 s26, s10, 1
	s_lshl_b32 s24, s24, 1
	s_or_b32 s24, s24, s26
	s_bfe_u32 s26, s10, 0x20001
	s_lshl_b32 s25, s25, 2
	s_or_b32 s25, s25, s26
	s_lshl_b32 s25, s25, 6
	s_lshl_b32 s24, s24, 5
	s_lshl_b32 s26, s9, s48
	s_lshl_b32 s27, s25, s15
	s_add_u32 s26, s26, s27
	s_lshl_b32 s27, s24, 2
	s_add_u32 s26, s26, s27
	s_add_u32 s20, s20, s26
	s_addc_u32 s21, s21, 0
	s_lshl_b32 s28, 1, s15
	s_lshl_b32 s26, s9, s17
	s_lshl_b32 s27, s24, 12
	s_add_u32 s26, s26, s27
	s_lshl_b32 s27, s25, 1
	s_add_u32 s26, s26, s27
	s_add_u32 s22, s22, s26
	s_addc_u32 s23, s23, 0
	s_lshl_b32 s26, s9, 13
	s_lshl_b32 s27, s25, 2
	s_add_u32 s26, s26, s27
	s_add_u32 s30, s82, s26
	s_addc_u32 s31, s83, 0
	v_cndmask_b32_e64 v6, v3, v2, s[12:13]
	global_load_dwordx4 v[48:51], v11, s[30:31]
	global_load_dwordx4 v[52:55], v11, s[30:31] offset:16
	global_load_dwordx4 v[16:19], v6, s[20:21] nt
	s_add_u32 s20, s20, s28
	s_addc_u32 s21, s21, 0
	global_load_dwordx4 v[20:23], v6, s[20:21] nt
	s_add_u32 s20, s20, s28
	s_addc_u32 s21, s21, 0
	global_load_dwordx4 v[24:27], v6, s[20:21] nt
	s_add_u32 s20, s20, s28
	s_addc_u32 s21, s21, 0
	global_load_dwordx4 v[28:31], v6, s[20:21] nt
	s_add_u32 s20, s20, s28
	s_addc_u32 s21, s21, 0
	global_load_dwordx4 v[32:35], v6, s[20:21] nt
	s_add_u32 s20, s20, s28
	s_addc_u32 s21, s21, 0
	global_load_dwordx4 v[36:39], v6, s[20:21] nt
	s_add_u32 s20, s20, s28
	s_addc_u32 s21, s21, 0
	global_load_dwordx4 v[40:43], v6, s[20:21] nt
	s_add_u32 s20, s20, s28
	s_addc_u32 s21, s21, 0
	global_load_dwordx4 v[44:47], v6, s[20:21] nt
	s_add_u32 s46, s7, 0x700
	s_sub_u32 s58, 3, s78
	s_mul_i32 s58, s58, 0x2800
	s_cmp_lt_u32 s46, s58
	s_cbranch_scc0 .Lgb_one
	s_mul_hi_u32 s9, s46, 0x66666667
	s_lshr_b32 s9, s9, 12
	s_mul_i32 s10, s9, 0x2800
	s_sub_u32 s10, s46, s10
	s_sub_u32 s9, 3, s9
	s_cmp_lt_u32 s10, 0x2000
	s_cselect_b64 s[50:51], -1, 0
	s_cselect_b32 s11, 0, 0x2000
	s_cselect_b32 s14, 7, 5
	s_cselect_b32 s15, 15, 13
	s_cselect_b32 s48, 26, 24
	s_cselect_b32 s17, 25, 23
	s_cselect_b32 s38, s84, s92
	s_cselect_b32 s39, s85, s93
	s_cselect_b32 s34, s40, s42
	s_cselect_b32 s35, s41, s43
	s_sub_u32 s10, s10, s11
	s_lshr_b32 s24, s10, 3
	s_lshr_b32 s25, s24, s14
	s_lshl_b32 s26, s25, s14
	s_sub_u32 s24, s24, s26
	s_and_b32 s26, s10, 1
	s_lshl_b32 s24, s24, 1
	s_or_b32 s24, s24, s26
	s_bfe_u32 s26, s10, 0x20001
	s_lshl_b32 s25, s25, 2
	s_or_b32 s25, s25, s26
	s_lshl_b32 s25, s25, 6
	s_lshl_b32 s24, s24, 5
	s_lshl_b32 s26, s9, s48
	s_lshl_b32 s27, s25, s15
	s_add_u32 s26, s26, s27
	s_lshl_b32 s27, s24, 2
	s_add_u32 s26, s26, s27
	s_add_u32 s38, s38, s26
	s_addc_u32 s39, s39, 0
	s_lshl_b32 s29, 1, s15
	s_lshl_b32 s26, s9, s17
	s_lshl_b32 s27, s24, 12
	s_add_u32 s26, s26, s27
	s_lshl_b32 s27, s25, 1
	s_add_u32 s26, s26, s27
	s_add_u32 s34, s34, s26
	s_addc_u32 s35, s35, 0
	s_lshl_b32 s26, s9, 13
	s_lshl_b32 s27, s25, 2
	s_add_u32 s26, s26, s27
	s_add_u32 s86, s82, s26
	s_addc_u32 s87, s83, 0
	v_cndmask_b32_e64 v7, v3, v2, s[50:51]
	global_load_dwordx4 v[96:99], v11, s[86:87]
	global_load_dwordx4 v[100:103], v11, s[86:87] offset:16
	global_load_dwordx4 v[64:67], v7, s[38:39] nt
	s_add_u32 s38, s38, s29
	s_addc_u32 s39, s39, 0
	global_load_dwordx4 v[68:71], v7, s[38:39] nt
	s_add_u32 s38, s38, s29
	s_addc_u32 s39, s39, 0
	global_load_dwordx4 v[72:75], v7, s[38:39] nt
	s_add_u32 s38, s38, s29
	s_addc_u32 s39, s39, 0
	global_load_dwordx4 v[76:79], v7, s[38:39] nt
	s_add_u32 s38, s38, s29
	s_addc_u32 s39, s39, 0
	global_load_dwordx4 v[80:83], v7, s[38:39] nt
	s_add_u32 s38, s38, s29
	s_addc_u32 s39, s39, 0
	global_load_dwordx4 v[84:87], v7, s[38:39] nt
	s_add_u32 s38, s38, s29
	s_addc_u32 s39, s39, 0
	global_load_dwordx4 v[88:91], v7, s[38:39] nt
	s_add_u32 s38, s38, s29
	s_addc_u32 s39, s39, 0
	global_load_dwordx4 v[92:95], v7, s[38:39] nt
	s_waitcnt vmcnt(10)
	s_cmp_eq_u64 s[12:13], 0
	s_cbranch_scc1 .Lgb_nomul_g
	v_mul_f32_e32 v16, v16, v48
	v_mul_f32_e32 v17, v17, v48
	v_mul_f32_e32 v18, v18, v48
	v_mul_f32_e32 v19, v19, v48
	v_mul_f32_e32 v20, v20, v49
	v_mul_f32_e32 v21, v21, v49
	v_mul_f32_e32 v22, v22, v49
	v_mul_f32_e32 v23, v23, v49
	v_mul_f32_e32 v24, v24, v50
	v_mul_f32_e32 v25, v25, v50
	v_mul_f32_e32 v26, v26, v50
	v_mul_f32_e32 v27, v27, v50
	v_mul_f32_e32 v28, v28, v51
	v_mul_f32_e32 v29, v29, v51
	v_mul_f32_e32 v30, v30, v51
	v_mul_f32_e32 v31, v31, v51
	v_mul_f32_e32 v32, v32, v52
	v_mul_f32_e32 v33, v33, v52
	v_mul_f32_e32 v34, v34, v52
	v_mul_f32_e32 v35, v35, v52
	v_mul_f32_e32 v36, v36, v53
	v_mul_f32_e32 v37, v37, v53
	v_mul_f32_e32 v38, v38, v53
	v_mul_f32_e32 v39, v39, v53
	v_mul_f32_e32 v40, v40, v54
	v_mul_f32_e32 v41, v41, v54
	v_mul_f32_e32 v42, v42, v54
	v_mul_f32_e32 v43, v43, v54
	v_mul_f32_e32 v44, v44, v55
	v_mul_f32_e32 v45, v45, v55
	v_mul_f32_e32 v46, v46, v55
	v_mul_f32_e32 v47, v47, v55
.Lgb_nomul_g:
	v_cvt_pk_bf16_f32 v112, v16, v20
	v_cvt_pk_bf16_f32 v113, v24, v28
	v_cvt_pk_bf16_f32 v114, v32, v36
	v_cvt_pk_bf16_f32 v115, v40, v44
	v_cvt_pk_bf16_f32 v116, v17, v21
	v_cvt_pk_bf16_f32 v117, v25, v29
	v_cvt_pk_bf16_f32 v118, v33, v37
	v_cvt_pk_bf16_f32 v119, v41, v45
	v_cvt_pk_bf16_f32 v120, v18, v22
	v_cvt_pk_bf16_f32 v121, v26, v30
	v_cvt_pk_bf16_f32 v122, v34, v38
	v_cvt_pk_bf16_f32 v123, v42, v46
	v_cvt_pk_bf16_f32 v124, v19, v23
	v_cvt_pk_bf16_f32 v125, v27, v31
	v_cvt_pk_bf16_f32 v126, v35, v39
	v_cvt_pk_bf16_f32 v127, v43, v47
	global_store_dwordx4 v5, v[112:115], s[22:23] nt
	s_add_u32 s22, s22, 0x1000
	s_addc_u32 s23, s23, 0
	global_store_dwordx4 v5, v[116:119], s[22:23] nt
	s_add_u32 s22, s22, 0x1000
	s_addc_u32 s23, s23, 0
	global_store_dwordx4 v5, v[120:123], s[22:23] nt
	s_add_u32 s22, s22, 0x1000
	s_addc_u32 s23, s23, 0
	global_store_dwordx4 v5, v[124:127], s[22:23] nt
	s_waitcnt vmcnt(0)
	s_cmp_eq_u64 s[50:51], 0
	s_cbranch_scc1 .Lgb_nomul_h
	v_mul_f32_e32 v64, v64, v96
	v_mul_f32_e32 v65, v65, v96
	v_mul_f32_e32 v66, v66, v96
	v_mul_f32_e32 v67, v67, v96
	v_mul_f32_e32 v68, v68, v97
	v_mul_f32_e32 v69, v69, v97
	v_mul_f32_e32 v70, v70, v97
	v_mul_f32_e32 v71, v71, v97
	v_mul_f32_e32 v72, v72, v98
	v_mul_f32_e32 v73, v73, v98
	v_mul_f32_e32 v74, v74, v98
	v_mul_f32_e32 v75, v75, v98
	v_mul_f32_e32 v76, v76, v99
	v_mul_f32_e32 v77, v77, v99
	v_mul_f32_e32 v78, v78, v99
	v_mul_f32_e32 v79, v79, v99
	v_mul_f32_e32 v80, v80, v100
	v_mul_f32_e32 v81, v81, v100
	v_mul_f32_e32 v82, v82, v100
	v_mul_f32_e32 v83, v83, v100
	v_mul_f32_e32 v84, v84, v101
	v_mul_f32_e32 v85, v85, v101
	v_mul_f32_e32 v86, v86, v101
	v_mul_f32_e32 v87, v87, v101
	v_mul_f32_e32 v88, v88, v102
	v_mul_f32_e32 v89, v89, v102
	v_mul_f32_e32 v90, v90, v102
	v_mul_f32_e32 v91, v91, v102
	v_mul_f32_e32 v92, v92, v103
	v_mul_f32_e32 v93, v93, v103
	v_mul_f32_e32 v94, v94, v103
	v_mul_f32_e32 v95, v95, v103
.Lgb_nomul_h:
	v_cvt_pk_bf16_f32 v112, v64, v68
	v_cvt_pk_bf16_f32 v113, v72, v76
	v_cvt_pk_bf16_f32 v114, v80, v84
	v_cvt_pk_bf16_f32 v115, v88, v92
	v_cvt_pk_bf16_f32 v116, v65, v69
	v_cvt_pk_bf16_f32 v117, v73, v77
	v_cvt_pk_bf16_f32 v118, v81, v85
	v_cvt_pk_bf16_f32 v119, v89, v93
	v_cvt_pk_bf16_f32 v120, v66, v70
	v_cvt_pk_bf16_f32 v121, v74, v78
	v_cvt_pk_bf16_f32 v122, v82, v86
	v_cvt_pk_bf16_f32 v123, v90, v94
	v_cvt_pk_bf16_f32 v124, v67, v71
	v_cvt_pk_bf16_f32 v125, v75, v79
	v_cvt_pk_bf16_f32 v126, v83, v87
	v_cvt_pk_bf16_f32 v127, v91, v95
	global_store_dwordx4 v5, v[112:115], s[34:35] nt
	s_add_u32 s34, s34, 0x1000
	s_addc_u32 s35, s35, 0
	global_store_dwordx4 v5, v[116:119], s[34:35] nt
	s_add_u32 s34, s34, 0x1000
	s_addc_u32 s35, s35, 0
	global_store_dwordx4 v5, v[120:123], s[34:35] nt
	s_add_u32 s34, s34, 0x1000
	s_addc_u32 s35, s35, 0
	global_store_dwordx4 v5, v[124:127], s[34:35] nt
	s_branch .Lgb_skip2
.Lgb_one:
	s_waitcnt vmcnt(0)
	s_cmp_eq_u64 s[12:13], 0
	s_cbranch_scc1 .Lgb_nomul_i
	v_mul_f32_e32 v16, v16, v48
	v_mul_f32_e32 v17, v17, v48
	v_mul_f32_e32 v18, v18, v48
	v_mul_f32_e32 v19, v19, v48
	v_mul_f32_e32 v20, v20, v49
	v_mul_f32_e32 v21, v21, v49
	v_mul_f32_e32 v22, v22, v49
	v_mul_f32_e32 v23, v23, v49
	v_mul_f32_e32 v24, v24, v50
	v_mul_f32_e32 v25, v25, v50
	v_mul_f32_e32 v26, v26, v50
	v_mul_f32_e32 v27, v27, v50
	v_mul_f32_e32 v28, v28, v51
	v_mul_f32_e32 v29, v29, v51
	v_mul_f32_e32 v30, v30, v51
	v_mul_f32_e32 v31, v31, v51
	v_mul_f32_e32 v32, v32, v52
	v_mul_f32_e32 v33, v33, v52
	v_mul_f32_e32 v34, v34, v52
	v_mul_f32_e32 v35, v35, v52
	v_mul_f32_e32 v36, v36, v53
	v_mul_f32_e32 v37, v37, v53
	v_mul_f32_e32 v38, v38, v53
	v_mul_f32_e32 v39, v39, v53
	v_mul_f32_e32 v40, v40, v54
	v_mul_f32_e32 v41, v41, v54
	v_mul_f32_e32 v42, v42, v54
	v_mul_f32_e32 v43, v43, v54
	v_mul_f32_e32 v44, v44, v55
	v_mul_f32_e32 v45, v45, v55
	v_mul_f32_e32 v46, v46, v55
	v_mul_f32_e32 v47, v47, v55

.Lgb_skip2:
.Lgb_skip:
	s_lshl_b32 s0, s78, 9
	s_mov_b32 s1, s63
	s_mov_b32 s2, s0
	v_writelane_b32 v255, s2, 45
	s_lshl_b64 s[0:1], s[0:1], 2
	s_add_u32 s86, s56, s0
	v_writelane_b32 v255, s3, 46
	s_addc_u32 s87, s57, s1
	v_readlane_b32 s2, v255, 14
	s_add_u32 s83, s2, s0
	v_readlane_b32 s0, v255, 15
	s_addc_u32 s82, s0, s1
	s_lshl_b32 s62, s78, 7
	v_readlane_b32 s0, v255, 26
	s_lshl_b64 s[84:85], s[62:63], 2
	v_readlane_b32 s6, v255, 32
	v_readlane_b32 s7, v255, 33
	s_add_u32 s88, s6, s84
	v_readlane_b32 s8, v255, 34
	s_addc_u32 s89, s7, s85
	v_readlane_b32 s1, v255, 27
	v_readlane_b32 s9, v255, 35
	s_add_u32 s90, s8, s84
	v_readlane_b32 s10, v255, 36
	s_addc_u32 s91, s9, s85
	s_mul_i32 s1, s78, 0x2800
	v_readlane_b32 s11, v255, 37
	s_mul_hi_u32 s0, s78, 0x2800
	s_add_u32 s92, s10, s1
	v_mov_b32_e32 v0, v243
	s_waitcnt lgkmcnt(0)
	s_barrier
	s_addc_u32 s93, s11, s0
	v_readlane_b32 s6, v255, 59
	s_cmp_lt_u32 s78, 3
	s_cbranch_scc0 .Lcv_skip
	s_cmp_lt_u32 s6, 0x400
	s_cbranch_scc0 .Lcv_skip
	s_add_u32 s6, s6, 0xe00
	v_readlane_b32 s2, v255, 57
	v_readlane_b32 s3, v255, 58
	v_readlane_b32 s4, v255, 53
	v_readlane_b32 s5, v255, 54
	v_readlane_b32 s18, v255, 60
	v_readlane_b32 s19, v255, 61
	v_readlane_b32 s40, v255, 6
	v_readlane_b32 s41, v255, 7
	v_readlane_b32 s42, v255, 8
	v_readlane_b32 s43, v255, 9
	v_and_b32_e32 v12, 63, v243
	v_lshrrev_b32_e32 v6, 3, v12
	v_and_b32_e32 v7, 7, v12
	v_lshlrev_b32_e32 v8, 4, v7
	v_lshl_or_b32 v2, v6, 18, v8
	v_lshl_or_b32 v3, v6, 16, v8
	v_lshlrev_b32_e32 v11, 5, v6
	v_lshlrev_b32_e32 v9, 4, v6
	v_lshl_or_b32 v5, v7, 14, v9
	s_sub_u32 s47, 1, s78
	s_mul_i32 s47, s47, 0x2800
	s_add_u32 s7, s47, s6
	s_add_u32 s59, s47, 0x2000
	s_add_u32 s47, s6, 0x2000
	s_sub_u32 s58, 3, s78
	s_mul_i32 s58, s58, 0x2800
	s_cmp_eq_u32 s78, 2
	s_cselect_b32 s59, 0x80000000, s59
	s_cselect_b32 s7, s47, s7
	s_cmp_lt_u32 s7, s58
	s_cbranch_scc0 .Lcv_skip
	s_mul_hi_u32 s9, s7, 0x66666667
	s_lshr_b32 s9, s9, 12
	s_mul_i32 s10, s9, 0x2800
	s_sub_u32 s10, s7, s10
	s_sub_u32 s9, 3, s9
	s_cmp_lt_u32 s10, 0x2000
	s_cselect_b64 s[12:13], -1, 0
	s_cselect_b32 s11, 0, 0x2000
	s_cselect_b32 s14, 7, 5
	s_cselect_b32 s15, 15, 13
	s_cselect_b32 s48, 26, 24
	s_cselect_b32 s17, 25, 23
	s_cselect_b32 s20, s4, s18
	s_cselect_b32 s21, s5, s19
	s_cselect_b32 s22, s40, s42
	s_cselect_b32 s23, s41, s43
	s_sub_u32 s10, s10, s11
	s_lshr_b32 s24, s10, 3
	s_lshr_b32 s25, s24, s14
	s_lshl_b32 s26, s25, s14
	s_sub_u32 s24, s24, s26
	s_and_b32 s26, s10, 1
	s_lshl_b32 s24, s24, 1
	s_or_b32 s24, s24, s26
	s_bfe_u32 s26, s10, 0x20001
	s_lshl_b32 s25, s25, 2
	s_or_b32 s25, s25, s26
	s_lshl_b32 s25, s25, 6
	s_lshl_b32 s24, s24, 5
	s_lshl_b32 s26, s9, s48
	s_lshl_b32 s27, s25, s15
	s_add_u32 s26, s26, s27
	s_lshl_b32 s27, s24, 2
	s_add_u32 s26, s26, s27
	s_add_u32 s20, s20, s26
	s_addc_u32 s21, s21, 0
	s_lshl_b32 s28, 1, s15
	s_lshl_b32 s26, s9, s17
	s_lshl_b32 s27, s24, 12
	s_add_u32 s26, s26, s27
	s_lshl_b32 s27, s25, 1
	s_add_u32 s26, s26, s27
	s_add_u32 s22, s22, s26
	s_addc_u32 s23, s23, 0
	s_lshl_b32 s26, s9, 13
	s_lshl_b32 s27, s25, 2
	s_add_u32 s26, s26, s27
	s_add_u32 s30, s2, s26
	s_addc_u32 s31, s3, 0
	v_cndmask_b32_e64 v6, v3, v2, s[12:13]
	global_load_dwordx4 v[48:51], v11, s[30:31]
	global_load_dwordx4 v[52:55], v11, s[30:31] offset:16
	global_load_dwordx4 v[16:19], v6, s[20:21] nt
	s_add_u32 s20, s20, s28
	s_addc_u32 s21, s21, 0
	global_load_dwordx4 v[20:23], v6, s[20:21] nt
	s_add_u32 s20, s20, s28
	s_addc_u32 s21, s21, 0
	global_load_dwordx4 v[24:27], v6, s[20:21] nt
	s_add_u32 s20, s20, s28
	s_addc_u32 s21, s21, 0
	global_load_dwordx4 v[28:31], v6, s[20:21] nt
	s_add_u32 s20, s20, s28
	s_addc_u32 s21, s21, 0
	global_load_dwordx4 v[32:35], v6, s[20:21] nt
	s_add_u32 s20, s20, s28
	s_addc_u32 s21, s21, 0
	global_load_dwordx4 v[36:39], v6, s[20:21] nt
	s_add_u32 s20, s20, s28
	s_addc_u32 s21, s21, 0
	global_load_dwordx4 v[40:43], v6, s[20:21] nt
	s_add_u32 s20, s20, s28
	s_addc_u32 s21, s21, 0
	global_load_dwordx4 v[44:47], v6, s[20:21] nt
	s_add_u32 s46, s7, 0x400
	s_sub_u32 s47, s46, s59
	s_cmp_lt_u32 s47, 0x400
	s_cselect_b32 s47, 0x2800, 0
	s_add_u32 s46, s46, s47
	s_cmp_lt_u32 s46, s58
	s_cbranch_scc0 .Lcv_nob0
	s_mul_hi_u32 s9, s46, 0x66666667
	s_lshr_b32 s9, s9, 12
	s_mul_i32 s10, s9, 0x2800
	s_sub_u32 s10, s46, s10
	s_sub_u32 s9, 3, s9
	s_cmp_lt_u32 s10, 0x2000
	s_cselect_b64 s[50:51], -1, 0
	s_cselect_b32 s11, 0, 0x2000
	s_cselect_b32 s14, 7, 5
	s_cselect_b32 s15, 15, 13
	s_cselect_b32 s48, 26, 24
	s_cselect_b32 s17, 25, 23
	s_cselect_b32 s38, s4, s18
	s_cselect_b32 s39, s5, s19
	s_cselect_b32 s34, s40, s42
	s_cselect_b32 s35, s41, s43
	s_sub_u32 s10, s10, s11
	s_lshr_b32 s24, s10, 3
	s_lshr_b32 s25, s24, s14
	s_lshl_b32 s26, s25, s14
	s_sub_u32 s24, s24, s26
	s_and_b32 s26, s10, 1
	s_lshl_b32 s24, s24, 1
	s_or_b32 s24, s24, s26
	s_bfe_u32 s26, s10, 0x20001
	s_lshl_b32 s25, s25, 2
	s_or_b32 s25, s25, s26
	s_lshl_b32 s25, s25, 6
	s_lshl_b32 s24, s24, 5
	s_lshl_b32 s26, s9, s48
	s_lshl_b32 s27, s25, s15
	s_add_u32 s26, s26, s27
	s_lshl_b32 s27, s24, 2
	s_add_u32 s26, s26, s27
	s_add_u32 s38, s38, s26
	s_addc_u32 s39, s39, 0
	s_lshl_b32 s29, 1, s15
	s_lshl_b32 s26, s9, s17
	s_lshl_b32 s27, s24, 12
	s_add_u32 s26, s26, s27
	s_lshl_b32 s27, s25, 1
	s_add_u32 s26, s26, s27
	s_add_u32 s34, s34, s26
	s_addc_u32 s35, s35, 0
	s_lshl_b32 s26, s9, 13
	s_lshl_b32 s27, s25, 2
	s_add_u32 s26, s26, s27
	s_add_u32 s56, s2, s26
	s_addc_u32 s57, s3, 0
	v_cndmask_b32_e64 v7, v3, v2, s[50:51]
	global_load_dwordx4 v[96:99], v11, s[56:57]
	global_load_dwordx4 v[100:103], v11, s[56:57] offset:16
	global_load_dwordx4 v[64:67], v7, s[38:39] nt
	s_add_u32 s38, s38, s29
	s_addc_u32 s39, s39, 0
	global_load_dwordx4 v[68:71], v7, s[38:39] nt
	s_add_u32 s38, s38, s29
	s_addc_u32 s39, s39, 0
	global_load_dwordx4 v[72:75], v7, s[38:39] nt
	s_add_u32 s38, s38, s29
	s_addc_u32 s39, s39, 0
	global_load_dwordx4 v[76:79], v7, s[38:39] nt
	s_add_u32 s38, s38, s29
	s_addc_u32 s39, s39, 0
	global_load_dwordx4 v[80:83], v7, s[38:39] nt
	s_add_u32 s38, s38, s29
	s_addc_u32 s39, s39, 0
	global_load_dwordx4 v[84:87], v7, s[38:39] nt
	s_add_u32 s38, s38, s29
	s_addc_u32 s39, s39, 0
	global_load_dwordx4 v[88:91], v7, s[38:39] nt
	s_add_u32 s38, s38, s29
	s_addc_u32 s39, s39, 0
	global_load_dwordx4 v[92:95], v7, s[38:39] nt
	s_waitcnt vmcnt(10)
	s_branch .Lcv_loop
